# P5 ssd_s3: hoist the 9 epilogue loads (x, z, d_skip) per head above the y_diag phase into free VGPRs; epilogue copies instead of 4 serialized load round trips
# speedup vs baseline: 1.0005x; 1.0005x over previous
; __device__ __forceinline__ unsigned pk2(float lo, float hi) { f32x2_t v = {lo, hi}; bf16x2_t b = __builtin_convertvector(v, bf16x2_t); return __builtin_bit_cast(unsigned, b); }
; __device__ __forceinline__ float bflo(unsigned u) { return __uint_as_float(u << 16); }
; __device__ __forceinline__ float bfhi(unsigned u) { return __uint_as_float(u & 0xffff0000u); }
; __device__ __forceinline__ float silu_f(float x) { return x * __builtin_amdgcn_rcpf(1.f + __builtin_amdgcn_exp2f(x * -1.4426950408889634f)); }
; __device__ __forceinline__ void ssd_s3_unit(const Params& p, int unit, unsigned char* ldsb) {
;     ...
;         const float dsk = p.d_skip[h];
;         const size_t row = (size_t)(row0 + lrow);
;         bfu* yg = (bfu*)(p.ws + WS_YG);
; #pragma unroll
;         for (int mt = 0; mt < 4; ++mt) {
;             const int pc = h * 64 + mt * 16 + quad * 4;
;             const uint2 xu = *(const uint2*)(xbc + row * 2048 + pc);
;             const uint2 zu = *(const uint2*)(proj + row * NPROJ + 3072 + pc);
;             const float y0 = (acc[mt][0] + dsk * bflo(xu.x)) * silu_f(bflo(zu.x)), y1 = (acc[mt][1] + dsk * bfhi(xu.x)) * silu_f(bfhi(zu.x));
;             const float y2 = (acc[mt][2] + dsk * bflo(xu.y)) * silu_f(bflo(zu.y)), y3 = (acc[mt][3] + dsk * bfhi(xu.y)) * silu_f(bfhi(zu.y));
;             uint2 o; o.x = pk2(y0, y1); o.y = pk2(y2, y3);
;             *(uint2*)(yg + row * 1024 + pc) = o;
;         }
.LBB0_542:
	s_waitcnt vmcnt(0)
	v_lshl_add_u64 v[50:51], s[88:89], 0, v[110:111]
	v_add_co_u32_e32 v50, vcc, 0x16800000, v50
	v_lshl_add_u64 v[206:207], s[88:89], 0, v[102:103]
	s_nop 0
	v_addc_co_u32_e32 v51, vcc, 0, v51, vcc
	v_add_co_u32_e32 v206, vcc, 0x4301000, v206
	v_mov_b64_e32 v[204:205], v[224:225]
	s_nop 0
	v_addc_co_u32_e32 v207, vcc, 0, v207, vcc
	v_mov_b64_e32 v[206:207], v[226:227]
	s_add_u32 s8, s96, s90
	s_addc_u32 s9, s6, s91
	v_mov_b32_e32 v48, v240
	s_mov_b32 s7, 0x22b00000
	s_add_u32 s90, s90, 4
	s_addc_u32 s91, s91, 0
	s_mov_b64 s[8:9], 0x4000
	v_lshl_add_u64 v[98:99], v[98:99], 0, s[8:9]
	v_add_u32_e32 v202, 0x4400, v202
	v_add_u32_e32 v201, 0x4400, v201
	v_add_u32_e32 v200, 0x4400, v200
	v_add_u32_e32 v199, 0x200, v199
	v_add_u32_e32 v198, 0x200, v198
	v_add_u32_e32 v197, 0x200, v197
	v_add_u32_e32 v193, 0x200, v193
	v_add_u32_e32 v192, 0x200, v192
	v_add_u32_e32 v191, 0x200, v191
	v_add_u32_e32 v190, 0x200, v190
	v_add_u32_e32 v189, 0x200, v189
	v_add_u32_e32 v188, 0x200, v188
	v_add_u32_e32 v187, 0x200, v187
	v_add_u32_e32 v186, 0x200, v186
	v_add_u32_e32 v185, 0x200, v185
	v_add_u32_e32 v184, 0x200, v184
	v_add_u32_e32 v183, 0x200, v183
	v_add_u32_e32 v182, 0x200, v182
	v_add_u32_e32 v181, 0x200, v181
	v_add_u32_e32 v178, 0x200, v178
	v_add_u32_e32 v171, 0x200, v171
	v_add_u32_e32 v170, 0x200, v170
	v_add_u32_e32 v169, 0x200, v169
	v_add_u32_e32 v168, 0x200, v168
	v_add_u32_e32 v167, 0x200, v167
	v_add_u32_e32 v166, 0x200, v166
	v_add_u32_e32 v165, 0x200, v165
	v_add_u32_e32 v164, 0x200, v164
	v_add_u32_e32 v163, 0x200, v163
	v_add_u32_e32 v97, 0x200, v97
	v_add_u32_e32 v95, 0x200, v95
	v_add_u32_e32 v93, 0x200, v93
	v_add_u32_e32 v91, 0x200, v91
	v_add_u32_e32 v89, 0x200, v89
	v_add_u32_e32 v87, 0x200, v87
	v_lshl_add_u64 v[110:111], v[110:111], 0, s[4:5]
	v_lshl_add_u64 v[102:103], v[102:103], 0, s[4:5]
	s_cmp_lg_u32 s90, 16
	v_lshlrev_b32_e32 v208, 16, v204
	v_and_b32_e32 v209, 0xffff0000, v204
	v_lshlrev_b32_e32 v204, 16, v205
	v_lshlrev_b32_e32 v210, 16, v206
	v_mul_f32_e32 v49, 0xbfb8aa3b, v210
	v_exp_f32_e32 v49, v49
	v_and_b32_e32 v211, 0xffff0000, v206
	v_lshlrev_b32_e32 v206, 16, v207
	v_and_b32_e32 v205, 0xffff0000, v205
	v_add_f32_e32 v49, 1.0, v49
	v_rcp_f32_e32 v212, v49
	v_pk_fma_f32 v[44:45], v[48:49], v[208:209], v[44:45] op_sel_hi:[0,1,1]
	v_mul_f32_e32 v49, 0xbfb8aa3b, v211
	v_exp_f32_e32 v49, v49
	v_and_b32_e32 v207, 0xffff0000, v207
	v_add_f32_e32 v49, 1.0, v49
	v_rcp_f32_e32 v213, v49
	v_mul_f32_e32 v49, 0xbfb8aa3b, v206
	v_exp_f32_e32 v49, v49
	v_pk_mul_f32 v[208:209], v[212:213], v[210:211]
	s_nop 0
	v_pk_mul_f32 v[44:45], v[44:45], v[208:209]
	v_add_f32_e32 v49, 1.0, v49
	v_rcp_f32_e32 v208, v49
	v_pk_fma_f32 v[46:47], v[48:49], v[204:205], v[46:47] op_sel_hi:[0,1,1]
	v_mul_f32_e32 v49, 0xbfb8aa3b, v207
	v_exp_f32_e32 v49, v49
	s_nop 0
	v_add_f32_e32 v49, 1.0, v49
	v_rcp_f32_e32 v209, v49
	s_nop 0
	v_pk_mul_f32 v[204:205], v[208:209], v[206:207]
	s_nop 0
	v_pk_mul_f32 v[46:47], v[46:47], v[204:205]
	v_cvt_pk_bf16_f32 v204, v44, v45
	v_lshl_add_u64 v[44:45], s[88:89], 0, v[100:101]
	v_add_co_u32_e32 v44, vcc, s7, v44
	v_cvt_pk_bf16_f32 v205, v46, v47
	s_nop 0
	v_addc_co_u32_e32 v45, vcc, 0, v45, vcc
	global_store_dwordx2 v[44:45], v[204:205], off
	v_lshl_add_u64 v[204:205], s[88:89], 0, v[108:109]
	v_add_co_u32_e32 v204, vcc, s3, v204
	v_mov_b64_e32 v[46:47], v[228:229]
	s_nop 0
	v_addc_co_u32_e32 v205, vcc, 0, v205, vcc
	v_mov_b64_e32 v[204:205], v[230:231]
	v_lshl_add_u64 v[100:101], v[100:101], 0, s[4:5]
	v_lshl_add_u64 v[108:109], v[108:109], 0, s[4:5]
	v_lshlrev_b32_e32 v206, 16, v46
	v_and_b32_e32 v207, 0xffff0000, v46
	v_pk_fma_f32 v[40:41], v[48:49], v[206:207], v[40:41] op_sel_hi:[0,1,1]
	v_lshlrev_b32_e32 v208, 16, v204
	v_mul_f32_e32 v46, 0xbfb8aa3b, v208
	v_exp_f32_e32 v46, v46
	v_and_b32_e32 v209, 0xffff0000, v204
	v_lshlrev_b32_e32 v204, 16, v205
	v_mul_f32_e32 v49, 0xbfb8aa3b, v204
	v_add_f32_e32 v46, 1.0, v46
	v_rcp_f32_e32 v210, v46
	v_mul_f32_e32 v46, 0xbfb8aa3b, v209
	v_exp_f32_e32 v46, v46
	v_exp_f32_e32 v49, v49
	v_and_b32_e32 v205, 0xffff0000, v205
	v_add_f32_e32 v46, 1.0, v46
	v_rcp_f32_e32 v211, v46
	v_lshlrev_b32_e32 v46, 16, v47
	v_and_b32_e32 v47, 0xffff0000, v47
	v_add_f32_e32 v49, 1.0, v49
	v_pk_fma_f32 v[42:43], v[48:49], v[46:47], v[42:43] op_sel_hi:[0,1,1]
	v_mul_f32_e32 v46, 0xbfb8aa3b, v205
	v_exp_f32_e32 v46, v46
	v_pk_mul_f32 v[206:207], v[210:211], v[208:209]
	v_add_f32_e32 v46, 1.0, v46
	v_pk_mul_f32 v[40:41], v[40:41], v[206:207]
	v_rcp_f32_e32 v206, v49
	v_rcp_f32_e32 v207, v46
	v_cvt_pk_bf16_f32 v40, v40, v41
	v_pk_mul_f32 v[46:47], v[206:207], v[204:205]
	s_nop 0
	v_pk_mul_f32 v[42:43], v[42:43], v[46:47]
	s_nop 0
	v_cvt_pk_bf16_f32 v41, v42, v43
	v_lshl_add_u64 v[42:43], s[88:89], 0, v[106:107]
	v_add_co_u32_e32 v42, vcc, s3, v42
	global_store_dwordx2 v[44:45], v[40:41], off offset:32
	s_nop 0
	v_addc_co_u32_e32 v43, vcc, 0, v43, vcc
	v_mov_b64_e32 v[40:41], v[232:233]
	v_lshl_add_u64 v[106:107], v[106:107], 0, s[4:5]
	v_mov_b64_e32 v[42:43], v[234:235]
	v_lshlrev_b32_e32 v46, 16, v40
	v_and_b32_e32 v47, 0xffff0000, v40
	v_lshlrev_b32_e32 v204, 16, v42
	v_mul_f32_e32 v40, 0xbfb8aa3b, v204
	v_exp_f32_e32 v40, v40
	v_and_b32_e32 v205, 0xffff0000, v42
	v_pk_fma_f32 v[36:37], v[48:49], v[46:47], v[36:37] op_sel_hi:[0,1,1]
	v_lshlrev_b32_e32 v42, 16, v43
	v_add_f32_e32 v40, 1.0, v40
	v_rcp_f32_e32 v206, v40
	v_mul_f32_e32 v40, 0xbfb8aa3b, v205
	v_exp_f32_e32 v40, v40
	v_and_b32_e32 v43, 0xffff0000, v43
	v_add_f32_e32 v40, 1.0, v40
	v_rcp_f32_e32 v207, v40
	v_lshlrev_b32_e32 v40, 16, v41
	v_and_b32_e32 v41, 0xffff0000, v41
; __device__ __forceinline__ unsigned pk2(float lo, float hi) { f32x2_t v = {lo, hi}; bf16x2_t b = __builtin_convertvector(v, bf16x2_t); return __builtin_bit_cast(unsigned, b); }
; __device__ __forceinline__ float bflo(unsigned u) { return __uint_as_float(u << 16); }
; __device__ __forceinline__ float bfhi(unsigned u) { return __uint_as_float(u & 0xffff0000u); }
; __device__ __forceinline__ float silu_f(float x) { return x * __builtin_amdgcn_rcpf(1.f + __builtin_amdgcn_exp2f(x * -1.4426950408889634f)); }
; #define MFMA16(a, b, c) __builtin_amdgcn_mfma_f32_16x16x32_bf16((a), (b), (c), 0, 0, 0)
; __device__ __forceinline__ void ssd_s3_unit(const Params& p, int unit, unsigned char* ldsb) {
;     ...
;         const bfu* hp = (const bfu*)(p.ws + WS_HPREV) + ((size_t)((b * 32 + c) * 16 + h) * 64) * 128;
;         bf16x8 hf[16];
; #pragma unroll
;         for (int i = 0; i < 16; ++i) hf[i] = ld8g(hp + (size_t)((i & 3) * 16 + l15) * 128 + (i >> 2) * 32 + quad * 8);
;         __builtin_amdgcn_sched_barrier(0);
; #pragma unroll
;         for (int ks = 0; ks < 4; ++ks) {
;             const bf16x8 bfr = *(const bf16x8*)(Cs + lrow * 136 + ks * 32 + quad * 8);
; #pragma unroll
;             for (int mt = 0; mt < 4; ++mt) acc[mt] = MFMA16(hf[ks * 4 + mt], bfr, acc[mt]);
;         }
;         const float el = __expf(csl);
; #pragma unroll
;         for (int mt = 0; mt < 4; ++mt) { acc[mt][0] *= el; acc[mt][1] *= el; acc[mt][2] *= el; acc[mt][3] *= el; }
;     ...
;         for (int mt = 0; mt < 4; ++mt) {
;             const int pc = h * 64 + mt * 16 + quad * 4;
;             const uint2 xu = *(const uint2*)(xbc + row * 2048 + pc);
;             const uint2 zu = *(const uint2*)(proj + row * NPROJ + 3072 + pc);
;             const float y0 = (acc[mt][0] + dsk * bflo(xu.x)) * silu_f(bflo(zu.x)), y1 = (acc[mt][1] + dsk * bfhi(xu.x)) * silu_f(bfhi(zu.x));
;             const float y2 = (acc[mt][2] + dsk * bflo(xu.y)) * silu_f(bflo(zu.y)), y3 = (acc[mt][3] + dsk * bfhi(xu.y)) * silu_f(bfhi(zu.y));
;             uint2 o; o.x = pk2(y0, y1); o.y = pk2(y2, y3);
;             *(uint2*)(yg + row * 1024 + pc) = o;
;         }
	v_pk_fma_f32 v[38:39], v[48:49], v[40:41], v[38:39] op_sel_hi:[0,1,1]
	v_pk_mul_f32 v[46:47], v[206:207], v[204:205]
	v_mul_f32_e32 v40, 0xbfb8aa3b, v43
	v_pk_mul_f32 v[36:37], v[36:37], v[46:47]
	v_mul_f32_e32 v46, 0xbfb8aa3b, v42
	v_exp_f32_e32 v46, v46
	v_exp_f32_e32 v40, v40
	v_cvt_pk_bf16_f32 v36, v36, v37
	v_add_f32_e32 v46, 1.0, v46
	v_add_f32_e32 v40, 1.0, v40
	v_rcp_f32_e32 v46, v46
	v_rcp_f32_e32 v47, v40
	s_nop 0
	v_pk_mul_f32 v[40:41], v[46:47], v[42:43]
	s_nop 0
	v_pk_mul_f32 v[38:39], v[38:39], v[40:41]
	s_nop 0
	v_cvt_pk_bf16_f32 v37, v38, v39
	v_lshl_add_u64 v[38:39], s[88:89], 0, v[104:105]
	v_add_co_u32_e32 v38, vcc, s3, v38
	global_store_dwordx2 v[44:45], v[36:37], off offset:64
	s_nop 0
	v_addc_co_u32_e32 v39, vcc, 0, v39, vcc
	v_mov_b64_e32 v[36:37], v[236:237]
	v_lshl_add_u64 v[104:105], v[104:105], 0, s[4:5]
	v_mov_b64_e32 v[38:39], v[238:239]
	v_lshlrev_b32_e32 v40, 16, v36
	v_and_b32_e32 v41, 0xffff0000, v36
	v_lshlrev_b32_e32 v42, 16, v38
	v_mul_f32_e32 v36, 0xbfb8aa3b, v42
	v_exp_f32_e32 v36, v36
	v_and_b32_e32 v43, 0xffff0000, v38
	v_pk_fma_f32 v[32:33], v[48:49], v[40:41], v[32:33] op_sel_hi:[0,1,1]
	v_lshlrev_b32_e32 v38, 16, v39
	v_add_f32_e32 v36, 1.0, v36
	v_rcp_f32_e32 v46, v36
	v_mul_f32_e32 v36, 0xbfb8aa3b, v43
	v_exp_f32_e32 v36, v36
	v_and_b32_e32 v39, 0xffff0000, v39
	v_add_f32_e32 v36, 1.0, v36
	v_rcp_f32_e32 v47, v36
	v_lshlrev_b32_e32 v36, 16, v37
	v_and_b32_e32 v37, 0xffff0000, v37
	v_pk_fma_f32 v[34:35], v[48:49], v[36:37], v[34:35] op_sel_hi:[0,1,1]
	v_pk_mul_f32 v[40:41], v[46:47], v[42:43]
	v_mul_f32_e32 v36, 0xbfb8aa3b, v39
	v_pk_mul_f32 v[32:33], v[32:33], v[40:41]
	v_mul_f32_e32 v40, 0xbfb8aa3b, v38
	v_exp_f32_e32 v40, v40
	v_exp_f32_e32 v36, v36
	v_cvt_pk_bf16_f32 v32, v32, v33
	v_add_f32_e32 v40, 1.0, v40
	v_add_f32_e32 v36, 1.0, v36
	v_rcp_f32_e32 v40, v40
	v_rcp_f32_e32 v41, v36
	s_nop 0
	v_pk_mul_f32 v[36:37], v[40:41], v[38:39]
	s_nop 0
	v_pk_mul_f32 v[34:35], v[34:35], v[36:37]
	s_nop 0
	v_cvt_pk_bf16_f32 v33, v34, v35
	global_store_dwordx2 v[44:45], v[32:33], off offset:96
	s_cbranch_scc0 .LBB0_524
.LBB0_543:
	v_lshl_add_u64 v[40:41], s[88:89], 0, v[98:99]
	s_mov_b32 s7, 0x20a00000
	v_add_co_u32_e32 v220, vcc, s7, v40
	s_mov_b32 s7, 0x20a01000
	s_nop 0
	v_addc_co_u32_e32 v221, vcc, 0, v41, vcc
	v_add_co_u32_e32 v228, vcc, s7, v40
	s_mov_b32 s7, 0x20a02000
	s_nop 0
	v_addc_co_u32_e32 v229, vcc, 0, v41, vcc
	v_add_co_u32_e32 v236, vcc, s7, v40
	s_mov_b32 s7, 0x20a03000
	s_nop 0
	v_addc_co_u32_e32 v237, vcc, 0, v41, vcc
	v_add_co_u32_e32 v244, vcc, s7, v40
	global_load_dwordx4 v[32:35], v[228:229], off offset:-4096
	global_load_dwordx4 v[36:39], v[228:229], off
	v_addc_co_u32_e32 v245, vcc, 0, v41, vcc
	global_load_dwordx4 v[40:43], v[244:245], off
	global_load_dwordx4 v[44:47], v[244:245], off offset:64
	global_load_dwordx4 v[48:51], v[220:221], off offset:64
	global_load_dwordx4 v[204:207], v[220:221], off offset:128
	global_load_dwordx4 v[208:211], v[228:229], off offset:64
	global_load_dwordx4 v[212:215], v[228:229], off offset:128
	global_load_dwordx4 v[216:219], v[236:237], off offset:64
	s_nop 0
	global_load_dwordx4 v[220:223], v[220:221], off offset:192
	s_nop 0
	global_load_dwordx4 v[224:227], v[244:245], off offset:-4096
	s_nop 0
	global_load_dwordx4 v[228:231], v[228:229], off offset:192
	s_nop 0
	global_load_dwordx4 v[232:235], v[236:237], off offset:128
	s_nop 0
	global_load_dwordx4 v[236:239], v[236:237], off offset:192
	s_nop 0
	global_load_dwordx4 v[240:243], v[244:245], off offset:128
	s_nop 0
	global_load_dwordx4 v[244:247], v[244:245], off offset:192
	v_add_u32_e32 v52, 0, v87
	ds_read_b32 v203, v52
	v_add_u32_e32 v52, v85, v176
	ds_read_b128 v[248:251], v52
	s_andn2_b64 vcc, exec, s[0:1]
	s_waitcnt vmcnt(15) lgkmcnt(0)
	v_mfma_f32_16x16x32_bf16 v[32:35], v[32:35], v[248:251], 0
	s_waitcnt vmcnt(14)
	v_mfma_f32_16x16x32_bf16 v[36:39], v[36:39], v[248:251], 0
	s_waitcnt vmcnt(5)
	v_mfma_f32_16x16x32_bf16 v[224:227], v[224:227], v[248:251], 0
	v_mfma_f32_16x16x32_bf16 v[40:43], v[40:43], v[248:251], 0
	ds_read_b128 v[248:251], v52 offset:64
	s_waitcnt lgkmcnt(0)
	v_mfma_f32_16x16x32_bf16 v[40:43], v[44:47], v[248:251], v[40:43]
	ds_read_b128 v[44:47], v52 offset:128
	v_mfma_f32_16x16x32_bf16 v[32:35], v[48:51], v[248:251], v[32:35]
	v_mfma_f32_16x16x32_bf16 v[36:39], v[208:211], v[248:251], v[36:39]
	ds_read_b128 v[208:211], v52 offset:192
	v_mfma_f32_16x16x32_bf16 v[48:51], v[216:219], v[248:251], v[224:227]
	s_waitcnt lgkmcnt(1)
	v_mfma_f32_16x16x32_bf16 v[36:39], v[212:215], v[44:47], v[36:39]
	s_waitcnt vmcnt(3)
	v_mfma_f32_16x16x32_bf16 v[48:51], v[232:235], v[44:47], v[48:51]
	v_mfma_f32_16x16x32_bf16 v[32:35], v[204:207], v[44:47], v[32:35]
	s_waitcnt vmcnt(1)
	v_mfma_f32_16x16x32_bf16 v[204:207], v[240:243], v[44:47], v[40:43]
	s_waitcnt lgkmcnt(0)
	v_mfma_f32_16x16x32_bf16 v[40:43], v[228:231], v[208:211], v[36:39]
	v_mfma_f32_16x16x32_bf16 v[36:39], v[236:239], v[208:211], v[48:51]
	s_nop 2
	v_mul_f32_e32 v48, 0x3fb8aa3b, v203
	v_add_u32_e32 v50, 0, v89
	v_exp_f32_e32 v52, v48
	v_add_u32_e32 v48, 0x22000, v50
	ds_read_b64 v[48:49], v48
	v_add_u32_e32 v50, 0x22800, v50
	ds_read_b64 v[50:51], v50
	v_mfma_f32_16x16x32_bf16 v[44:47], v[220:223], v[208:211], v[32:35]
	v_mul_f32_e64 v42, v52, v42
	v_mul_f32_e64 v43, v52, v43
	s_waitcnt lgkmcnt(1)
	v_sub_f32_e32 v48, v203, v48
	v_mul_f32_e32 v48, 0x3fb8aa3b, v48
	v_exp_f32_e32 v48, v48
	s_waitcnt vmcnt(0)
; __device__ __forceinline__ unsigned pk2(float lo, float hi) { f32x2_t v = {lo, hi}; bf16x2_t b = __builtin_convertvector(v, bf16x2_t); return __builtin_bit_cast(unsigned, b); }
; #define MFMA16(a, b, c) __builtin_amdgcn_mfma_f32_16x16x32_bf16((a), (b), (c), 0, 0, 0)
; __device__ __forceinline__ void ssd_s3_unit(const Params& p, int unit, unsigned char* ldsb) {
;     ...
;         for (int kk = 0; kk < 4; ++kk) {
;             if (2 * kk <= wave) {
;                 float mv[8];
; #pragma unroll
;                 for (int j = 0; j < 8; ++j) {
;                     const int tile = 2 * kk + (j >> 2), s = tile * 16 + quad * 4 + (j & 3);
;                     const float cbv = cbt[tile][j & 3];
;                     const float e = __expf(csl - csb[hh * 128 + s]) * dtb[hh * 128 + s];
;                     mv[j] = (s <= lrow) ? cbv * e : 0.f;
;                 }
;                 uint4 pu; pu.x = pk2(mv[0], mv[1]); pu.y = pk2(mv[2], mv[3]); pu.z = pk2(mv[4], mv[5]); pu.w = pk2(mv[6], mv[7]);
;                 const bf16x8 pf = __builtin_bit_cast(bf16x8, pu);
; #pragma unroll
;                 for (int mt = 0; mt < 4; ++mt) {
;                     const bfu* xp = XT + (mt * 16 + l15) * 136 + 32 * kk + quad * 4;
;                     acc[mt] = MFMA16(mk8(*(const uint2*)xp, *(const uint2*)(xp + 16)), pf, acc[mt]);
;                 }
;     ...
;         const float dsk = p.d_skip[h];
;         const size_t row = (size_t)(row0 + lrow);
;         bfu* yg = (bfu*)(p.ws + WS_YG);
; #pragma unroll
;         for (int mt = 0; mt < 4; ++mt) {
;             const int pc = h * 64 + mt * 16 + quad * 4;
;             const uint2 xu = *(const uint2*)(xbc + row * 2048 + pc);
;             const uint2 zu = *(const uint2*)(proj + row * NPROJ + 3072 + pc);
	v_mfma_f32_16x16x32_bf16 v[32:35], v[244:247], v[208:211], v[204:207]
	s_mov_b64 s[98:99], 0x16800000
	s_mov_b64 s[100:101], 0x4301000
	v_lshl_add_u64 v[214:215], s[88:89], 0, v[110:111]
	v_lshl_add_u64 v[216:217], s[88:89], 0, v[102:103]
	v_lshl_add_u64 v[218:219], s[88:89], 0, v[108:109]
	v_lshl_add_u64 v[220:221], s[88:89], 0, v[106:107]
	v_lshl_add_u64 v[222:223], s[88:89], 0, v[104:105]
	v_lshl_add_u64 v[214:215], v[214:215], 0, s[98:99]
	v_lshl_add_u64 v[216:217], v[216:217], 0, s[100:101]
	v_lshl_add_u64 v[218:219], v[218:219], 0, s[100:101]
	v_lshl_add_u64 v[220:221], v[220:221], 0, s[100:101]
	v_lshl_add_u64 v[222:223], v[222:223], 0, s[100:101]
	s_add_u32 s10, s96, s90
	s_addc_u32 s11, s6, s91
	global_load_dwordx2 v[224:225], v[214:215], off
	global_load_dwordx2 v[226:227], v[216:217], off offset:2048
	global_load_dword v240, v53, s[10:11]
	global_load_dwordx2 v[228:229], v[214:215], off offset:32
	global_load_dwordx2 v[230:231], v[218:219], off offset:2048
	global_load_dwordx2 v[232:233], v[214:215], off offset:64
	global_load_dwordx2 v[234:235], v[220:221], off offset:2048
	global_load_dwordx2 v[236:237], v[214:215], off offset:96
	global_load_dwordx2 v[238:239], v[222:223], off offset:2048
	v_mul_f32_e64 v46, v52, v46
	v_mul_f32_e64 v47, v52, v47
	v_pk_mul_f32 v[44:45], v[52:53], v[44:45] op_sel_hi:[0,1]
	s_waitcnt lgkmcnt(0)
	v_mul_f32_e32 v48, v50, v48
	v_mul_f32_e32 v48, v0, v48
	v_cndmask_b32_e64 v208, v48, 0, s[20:21]
	v_sub_f32_e32 v48, v203, v49
	v_mul_f32_e32 v48, 0x3fb8aa3b, v48
	v_exp_f32_e32 v48, v48
	v_add_u32_e32 v49, 0, v91
	v_add_u32_e32 v50, 0x22800, v49
	v_pk_mul_f32 v[40:41], v[52:53], v[40:41] op_sel_hi:[0,1]
	v_mul_f32_e32 v48, v51, v48
	v_mul_f32_e32 v48, v1, v48
	v_cndmask_b32_e64 v209, 0, v48, s[22:23]
	v_add_u32_e32 v48, 0x22000, v49
	v_add_u32_e32 v49, 0, v182
	ds_read_b32 v48, v48
	ds_read_b32 v49, v49
	ds_read_b64 v[50:51], v50
	v_pk_mul_f32 v[38:39], v[52:53], v[38:39] op_sel_hi:[0,1]
	v_pk_mul_f32 v[36:37], v[52:53], v[36:37] op_sel_hi:[0,1]
	s_waitcnt lgkmcnt(2)
	v_sub_f32_e32 v48, v203, v48
	s_waitcnt lgkmcnt(1)
	v_sub_f32_e32 v49, v203, v49
	v_mul_f32_e32 v48, 0x3fb8aa3b, v48
	v_mul_f32_e32 v49, 0x3fb8aa3b, v49
	v_exp_f32_e32 v48, v48
	v_exp_f32_e32 v49, v49
	v_pk_mul_f32 v[34:35], v[52:53], v[34:35] op_sel_hi:[0,1]
	v_pk_mul_f32 v[32:33], v[52:53], v[32:33] op_sel_hi:[0,1]
	s_waitcnt lgkmcnt(0)
	v_pk_mul_f32 v[48:49], v[50:51], v[48:49]
	s_nop 0
	v_pk_mul_f32 v[50:51], v[2:3], v[48:49]
	v_add_u32_e32 v49, 0, v93
	v_add_u32_e32 v48, 0x22000, v49
	v_add_u32_e32 v204, 0x22800, v49
	v_add_u32_e32 v49, 0, v183
	ds_read_b32 v48, v48
	ds_read_b32 v49, v49
	ds_read_b64 v[204:205], v204
	s_waitcnt lgkmcnt(2)
	v_sub_f32_e32 v48, v203, v48
	s_waitcnt lgkmcnt(1)
	v_sub_f32_e32 v49, v203, v49
	v_mul_f32_e32 v48, 0x3fb8aa3b, v48
	v_mul_f32_e32 v49, 0x3fb8aa3b, v49
	v_exp_f32_e32 v48, v48
	v_exp_f32_e32 v49, v49
	s_waitcnt lgkmcnt(0)
	v_pk_mul_f32 v[48:49], v[204:205], v[48:49]
	s_nop 0
	v_pk_mul_f32 v[204:205], v[8:9], v[48:49]
	v_add_u32_e32 v49, 0, v95
	v_add_u32_e32 v48, 0x22000, v49
	v_add_u32_e32 v206, 0x22800, v49
	v_add_u32_e32 v49, 0, v184
	ds_read_b32 v48, v48
	ds_read_b32 v49, v49
	ds_read_b64 v[206:207], v206
	s_waitcnt lgkmcnt(2)
	v_sub_f32_e32 v48, v203, v48
	s_waitcnt lgkmcnt(1)
	v_sub_f32_e32 v49, v203, v49
	v_mul_f32_e32 v48, 0x3fb8aa3b, v48
	v_mul_f32_e32 v49, 0x3fb8aa3b, v49
	v_exp_f32_e32 v48, v48
	v_exp_f32_e32 v49, v49
	s_waitcnt lgkmcnt(0)
	v_pk_mul_f32 v[48:49], v[206:207], v[48:49]
	s_nop 0
	v_pk_mul_f32 v[206:207], v[10:11], v[48:49]
	v_cvt_pk_bf16_f32 v49, v50, v51
	v_cndmask_b32_e64 v50, v49, 0, s[26:27]
	v_lshrrev_b32_e32 v49, 16, v49
	v_cndmask_b32_e64 v49, v49, 0, s[24:25]
	v_perm_b32 v49, v49, v50, s33
	v_cvt_pk_bf16_f32 v50, v204, v205
	v_cndmask_b32_e64 v51, v50, 0, s[30:31]
	v_lshrrev_b32_e32 v50, 16, v50
	v_cndmask_b32_e64 v50, v50, 0, s[28:29]
	v_perm_b32 v50, v50, v51, s33
	v_cvt_pk_bf16_f32 v51, v206, v207
	v_cndmask_b32_e64 v204, v51, 0, s[36:37]
	v_lshrrev_b32_e32 v51, 16, v51
	v_cndmask_b32_e64 v51, v51, 0, s[34:35]
	v_perm_b32 v51, v51, v204, s33
	v_add_u32_e32 v204, 0, v200
	v_add_u32_e32 v205, 0x11000, v204
	ds_read_b64 v[206:207], v205
	v_add_u32_e32 v205, 0x11020, v204
	v_cvt_pk_bf16_f32 v48, v208, v209
	ds_read_b64 v[208:209], v205
	v_add_u32_e32 v205, 0, v201
	s_waitcnt lgkmcnt(0)
	v_mfma_f32_16x16x32_bf16 v[44:47], v[206:209], v[48:51], v[44:47]
	v_add_u32_e32 v206, 0x11000, v205
	v_add_u32_e32 v208, 0x11020, v205
	ds_read_b64 v[206:207], v206
	ds_read_b64 v[208:209], v208
	s_waitcnt lgkmcnt(0)
	v_mfma_f32_16x16x32_bf16 v[40:43], v[206:209], v[48:51], v[40:43]
	v_add_u32_e32 v206, 0, v202
	ds_read2_b64 v[208:211], v206 offset1:4
	v_add_u32_e32 v207, 0x1000, v206
	s_waitcnt lgkmcnt(0)
	v_mfma_f32_16x16x32_bf16 v[36:39], v[208:211], v[48:51], v[36:39]
	ds_read2_b64 v[208:211], v207 offset0:32 offset1:36
	s_waitcnt lgkmcnt(0)
	v_mfma_f32_16x16x32_bf16 v[32:35], v[208:211], v[48:51], v[32:35]
	s_cbranch_vccnz .LBB0_546
; __device__ __forceinline__ unsigned pk2(float lo, float hi) { f32x2_t v = {lo, hi}; bf16x2_t b = __builtin_convertvector(v, bf16x2_t); return __builtin_bit_cast(unsigned, b); }
; #define MFMA16(a, b, c) __builtin_amdgcn_mfma_f32_16x16x32_bf16((a), (b), (c), 0, 0, 0)
; __device__ __forceinline__ void ssd_s3_unit(const Params& p, int unit, unsigned char* ldsb) {
;     ...
;         for (int kk = 0; kk < 4; ++kk) {
;             if (2 * kk <= wave) {
;                 float mv[8];
; #pragma unroll
;                 for (int j = 0; j < 8; ++j) {
;                     const int tile = 2 * kk + (j >> 2), s = tile * 16 + quad * 4 + (j & 3);
;                     const float cbv = cbt[tile][j & 3];
;                     const float e = __expf(csl - csb[hh * 128 + s]) * dtb[hh * 128 + s];
;                     mv[j] = (s <= lrow) ? cbv * e : 0.f;
;                 }
;                 uint4 pu; pu.x = pk2(mv[0], mv[1]); pu.y = pk2(mv[2], mv[3]); pu.z = pk2(mv[4], mv[5]); pu.w = pk2(mv[6], mv[7]);
;                 const bf16x8 pf = __builtin_bit_cast(bf16x8, pu);
; #pragma unroll
;                 for (int mt = 0; mt < 4; ++mt) {
;                     const bfu* xp = XT + (mt * 16 + l15) * 136 + 32 * kk + quad * 4;
;                     acc[mt] = MFMA16(mk8(*(const uint2*)xp, *(const uint2*)(xp + 16)), pf, acc[mt]);
;                 }
	v_add_u32_e32 v49, 0, v97
	v_add_u32_e32 v48, 0x22000, v49
	v_add_u32_e32 v50, 0x22800, v49
	v_add_u32_e32 v49, 0, v185
	ds_read_b32 v48, v48
	ds_read_b32 v49, v49
	ds_read_b64 v[50:51], v50
	s_waitcnt lgkmcnt(2)
	v_sub_f32_e32 v48, v203, v48
	s_waitcnt lgkmcnt(1)
	v_sub_f32_e32 v49, v203, v49
	v_mul_f32_e32 v48, 0x3fb8aa3b, v48
	v_mul_f32_e32 v49, 0x3fb8aa3b, v49
	v_exp_f32_e32 v48, v48
	v_exp_f32_e32 v49, v49
	s_waitcnt lgkmcnt(0)
	v_pk_mul_f32 v[48:49], v[50:51], v[48:49]
	v_add_u32_e32 v51, 0, v163
	v_add_u32_e32 v50, 0x22000, v51
	v_add_u32_e32 v52, 0x22800, v51
	v_add_u32_e32 v51, 0, v186
	ds_read_b32 v50, v50
	ds_read_b32 v51, v51
	ds_read_b64 v[208:209], v52
	v_add_u32_e32 v52, 0, v164
	v_pk_mul_f32 v[48:49], v[12:13], v[48:49]
	s_waitcnt lgkmcnt(2)
	v_sub_f32_e32 v50, v203, v50
	s_waitcnt lgkmcnt(1)
	v_sub_f32_e32 v51, v203, v51
	v_mul_f32_e32 v50, 0x3fb8aa3b, v50
	v_mul_f32_e32 v51, 0x3fb8aa3b, v51
	v_exp_f32_e32 v50, v50
	v_exp_f32_e32 v51, v51
	v_cvt_pk_bf16_f32 v48, v48, v49
	v_cndmask_b32_e64 v49, v48, 0, s[40:41]
	v_lshrrev_b32_e32 v48, 16, v48
	s_waitcnt lgkmcnt(0)
	v_pk_mul_f32 v[50:51], v[208:209], v[50:51]
	v_add_u32_e32 v208, 0x22000, v52
	v_add_u32_e32 v209, 0, v187
	ds_read_b32 v208, v208
	ds_read_b32 v209, v209
	v_add_u32_e32 v52, 0x22800, v52
	ds_read_b64 v[210:211], v52
	v_add_u32_e32 v52, 0, v165
	s_waitcnt lgkmcnt(2)
	v_sub_f32_e32 v208, v203, v208
	s_waitcnt lgkmcnt(1)
	v_sub_f32_e32 v209, v203, v209
	v_mul_f32_e32 v208, 0x3fb8aa3b, v208
	v_mul_f32_e32 v209, 0x3fb8aa3b, v209
	v_exp_f32_e32 v208, v208
	v_exp_f32_e32 v209, v209
	v_pk_mul_f32 v[50:51], v[14:15], v[50:51]
	v_cndmask_b32_e64 v48, v48, 0, s[38:39]
	v_perm_b32 v48, v48, v49, s33
	s_waitcnt lgkmcnt(0)
	v_pk_mul_f32 v[208:209], v[210:211], v[208:209]
	v_add_u32_e32 v210, 0x22000, v52
	v_add_u32_e32 v211, 0, v188
	ds_read_b32 v210, v210
	ds_read_b32 v211, v211
	v_add_u32_e32 v52, 0x22800, v52
	ds_read_b64 v[212:213], v52
	v_cvt_pk_bf16_f32 v49, v50, v51
	s_waitcnt lgkmcnt(2)
	v_sub_f32_e32 v210, v203, v210
	s_waitcnt lgkmcnt(1)
	v_sub_f32_e32 v211, v203, v211
	v_mul_f32_e32 v210, 0x3fb8aa3b, v210
	v_mul_f32_e32 v211, 0x3fb8aa3b, v211
	v_exp_f32_e32 v210, v210
	v_exp_f32_e32 v211, v211
	v_cndmask_b32_e64 v50, v49, 0, s[44:45]
	v_lshrrev_b32_e32 v49, 16, v49
	v_pk_mul_f32 v[208:209], v[4:5], v[208:209]
	v_cndmask_b32_e64 v49, v49, 0, s[42:43]
	v_perm_b32 v49, v49, v50, s33
	v_cvt_pk_bf16_f32 v50, v208, v209
	s_waitcnt lgkmcnt(0)
	v_pk_mul_f32 v[210:211], v[212:213], v[210:211]
	v_cndmask_b32_e64 v51, v50, 0, s[48:49]
	v_lshrrev_b32_e32 v50, 16, v50
	v_pk_mul_f32 v[210:211], v[6:7], v[210:211]
	v_cndmask_b32_e64 v50, v50, 0, s[46:47]
	v_perm_b32 v50, v50, v51, s33
	v_cvt_pk_bf16_f32 v51, v210, v211
	v_cndmask_b32_e64 v52, v51, 0, s[52:53]
	v_lshrrev_b32_e32 v51, 16, v51
	v_cndmask_b32_e64 v51, v51, 0, s[50:51]
	v_perm_b32 v51, v51, v52, s33
	v_add_u32_e32 v52, 0x11040, v204
	ds_read_b64 v[208:209], v52
	v_add_u32_e32 v52, 0x11060, v204
	ds_read_b64 v[210:211], v52
	v_add_u32_e32 v52, 0x11040, v205
	s_waitcnt lgkmcnt(0)
	v_mfma_f32_16x16x32_bf16 v[44:47], v[208:211], v[48:51], v[44:47]
	ds_read_b64 v[208:209], v52
	v_add_u32_e32 v52, 0x11060, v205
	ds_read_b64 v[210:211], v52
	s_waitcnt lgkmcnt(0)
	v_mfma_f32_16x16x32_bf16 v[40:43], v[208:211], v[48:51], v[40:43]
	ds_read2_b64 v[208:211], v206 offset0:8 offset1:12
	s_waitcnt lgkmcnt(0)
	v_mfma_f32_16x16x32_bf16 v[36:39], v[208:211], v[48:51], v[36:39]
	ds_read2_b64 v[208:211], v207 offset0:40 offset1:44
	s_waitcnt lgkmcnt(0)
	v_mfma_f32_16x16x32_bf16 v[32:35], v[208:211], v[48:51], v[32:35]
	s_andn2_b64 vcc, exec, s[94:95]
	s_cbranch_vccz .LBB0_547

; #define KP (kparams())
; __global__ void __launch_bounds__(512) fwd_kernel(Params p_unused) {
;     extern __shared__ __attribute__((aligned(16))) unsigned char smem[];
;     cg::grid_group grid = cg::this_grid();
;     const int G = gridDim.x, bid = blockIdx.x;
;     unsigned char* ws = KP.ws;
	.amdhsa_kernel _Z10fwd_kernel6Params
		.amdhsa_group_segment_fixed_size 0
		.amdhsa_private_segment_fixed_size 0
		.amdhsa_kernarg_size 448
		.amdhsa_user_sgpr_count 2
		.amdhsa_user_sgpr_dispatch_ptr 0
		.amdhsa_user_sgpr_queue_ptr 0
		.amdhsa_user_sgpr_kernarg_segment_ptr 1
		.amdhsa_user_sgpr_dispatch_id 0
		.amdhsa_user_sgpr_kernarg_preload_length 0
		.amdhsa_user_sgpr_kernarg_preload_offset 0
		.amdhsa_user_sgpr_private_segment_size 0
		.amdhsa_uses_dynamic_stack 0
		.amdhsa_enable_private_segment 0
		.amdhsa_system_sgpr_workgroup_id_x 1
		.amdhsa_system_sgpr_workgroup_id_y 0
		.amdhsa_system_sgpr_workgroup_id_z 0
		.amdhsa_system_sgpr_workgroup_info 0
		.amdhsa_system_vgpr_workitem_id 2
		.amdhsa_next_free_vgpr 253
		.amdhsa_next_free_sgpr 102
		.amdhsa_accum_offset 256
		.amdhsa_reserve_vcc 1
		.amdhsa_float_round_mode_32 0
		.amdhsa_float_round_mode_16_64 0
		.amdhsa_float_denorm_mode_32 3
		.amdhsa_float_denorm_mode_16_64 3
		.amdhsa_dx10_clamp 1
		.amdhsa_ieee_mode 1
		.amdhsa_fp16_overflow 0
		.amdhsa_tg_split 0
		.amdhsa_exception_fp_ieee_invalid_op 0
		.amdhsa_exception_fp_denorm_src 0
		.amdhsa_exception_fp_ieee_div_zero 0
		.amdhsa_exception_fp_ieee_overflow 0
		.amdhsa_exception_fp_ieee_underflow 0
		.amdhsa_exception_fp_ieee_inexact 0
		.amdhsa_exception_int_div_zero 0
	.end_amdhsa_kernel

; #define KP (kparams())
; __global__ void __launch_bounds__(512) fwd_kernel(Params p_unused) {
;     extern __shared__ __attribute__((aligned(16))) unsigned char smem[];
;     cg::grid_group grid = cg::this_grid();
;     const int G = gridDim.x, bid = blockIdx.x;
;     unsigned char* ws = KP.ws;
amdhsa.kernels:
  - .agpr_count:     0
    .args:
      - .offset:         0
        .size:           192
        .value_kind:     by_value
      - .offset:         192
        .size:           4
        .value_kind:     hidden_block_count_x
      - .offset:         196
        .size:           4
        .value_kind:     hidden_block_count_y
      - .offset:         200
        .size:           4
        .value_kind:     hidden_block_count_z
      - .offset:         204
        .size:           2
        .value_kind:     hidden_group_size_x
      - .offset:         206
        .size:           2
        .value_kind:     hidden_group_size_y
      - .offset:         208
        .size:           2
        .value_kind:     hidden_group_size_z
      - .offset:         210
        .size:           2
        .value_kind:     hidden_remainder_x
      - .offset:         212
        .size:           2
        .value_kind:     hidden_remainder_y
      - .offset:         214
        .size:           2
        .value_kind:     hidden_remainder_z
      - .offset:         232
        .size:           8
        .value_kind:     hidden_global_offset_x
      - .offset:         240
        .size:           8
        .value_kind:     hidden_global_offset_y
      - .offset:         248
        .size:           8
        .value_kind:     hidden_global_offset_z
      - .offset:         256
        .size:           2
        .value_kind:     hidden_grid_dims
      - .offset:         280
        .size:           8
        .value_kind:     hidden_multigrid_sync_arg
      - .offset:         312
        .size:           4
        .value_kind:     hidden_dynamic_lds_size
    .group_segment_fixed_size: 0
    .kernarg_segment_align: 8
    .kernarg_segment_size: 448
    .language:       OpenCL C
    .language_version:
      - 2
      - 0
    .max_flat_workgroup_size: 512
    .name:           _Z10fwd_kernel6Params
    .private_segment_fixed_size: 0
    .sgpr_count:     108
    .sgpr_spill_count: 22
    .symbol:         _Z10fwd_kernel6Params.kd
    .uniform_work_group_size: 1
    .uses_dynamic_stack: false
    .vgpr_count:     253
    .vgpr_spill_count: 0
    .wavefront_size: 64
